# v43 + prep item order: blocks >= 64 run their DFT item in slot (blockIdx & 3), light items in the other slots (DFT items spread over four time slots)
# speedup vs baseline: 1.0018x; 1.0018x over previous
; __device__ __forceinline__ int opaque_tid() { int t = threadIdx.x; asm volatile("" : "+v"(t)); return t; }
; __device__ __forceinline__ void phase_prep(const Params& P, int l, unsigned char* lds) {
;     ...
;     for (int item = blockIdx.x; item < ROWS / 64 + NBATCH * 20; item += G) {
;         const int tid = opaque_tid();
;         const int type = item >= ROWS / 64;
;         int r0, b, t0;
;         if (!type) { r0 = item * 64; b = r0 / TT; t0 = r0 - b * TT; }
;         else { const int idx = item - ROWS / 64; b = idx / 20; const int jb = idx - b * 20; t0 = (jb < 4) ? 64 * jb : CTX + 64 * (jb - 4); r0 = b * TT + t0; }
;         const bool is_ctx = t0 < CTX;
.LBB0_228:
	s_mov_b32 s101, s28
	s_cmp_lg_u32 s60, 0x100
	s_cbranch_scc1 .Lprep_map_done
	s_and_b32 s100, s28, 0xff
	s_lshr_b32 s101, s28, 8
	v_readlane_b32 vcc_lo, v255, 0
	s_nop 3
	s_cmp_eq_u32 vcc_lo, 3
	s_cbranch_scc1 .Lprep_last
	s_cmp_lt_u32 s100, 0x40
	s_cbranch_scc1 .Lprep_std
	s_and_b32 vcc_lo, s100, 3
	s_cmp_eq_u32 s101, vcc_lo
	s_cbranch_scc1 .Lprep_a0
	s_cmp_gt_u32 s101, vcc_lo
	s_cselect_b32 vcc_hi, 1, 0
	s_sub_u32 s101, s101, vcc_hi
	s_mul_i32 s101, s101, 0xc0
	s_add_u32 s101, s101, s100
	s_sub_u32 s101, s101, 0x40
	s_branch .Lprep_map_done
